# speedup vs baseline: 1.0175x; 1.0060x over previous
; DEVI int lbid() { int t = blockIdx.x; asm volatile("" : "+s"(t)); return t; }
; DEVI int lgdim() { int t = gridDim.x; asm volatile("" : "+s"(t)); return t; }
; DEVI void lru_p2_phase(const Params& p, char* lds) {
;     ...
;   for (int it = lbid(); it < 32; it += lgdim()) {
;     const int db = it >> 3, ch = (it & 7) * 128 + chl;
;     const size_t base = ((size_t)db * NCH64B + sg * 65) * 1024 + ch;
;     float h = 0.f, P = 0.f;
; #pragma unroll 13
;     for (int i = 0; i < 65; ++i) { const float Pc = AGP[base + (size_t)i * 1024], Bc = AGB[base + (size_t)i * 1024]; h = __expf(Pc) * h + Bc; P += Pc; }
.LBB0_1127:
	v_lshl_add_u64 v[6:7], v[4:5], 0, s[2:3]
	s_add_u32 s2, s2, 0xd000
	s_addc_u32 s3, s3, 0
	v_add_co_u32_e32 v16, vcc, 0x2db60000, v6
	s_nop 1
	v_addc_co_u32_e32 v17, vcc, 0, v7, vcc
	global_load_dword v20, v[16:17], off
	v_add_co_u32_e32 v16, vcc, 0x2df70000, v6
	s_nop 1
	v_addc_co_u32_e32 v17, vcc, 0, v7, vcc
	global_load_dword v21, v[16:17], off
	v_add_co_u32_e32 v16, vcc, 0x2db61000, v6
	s_nop 1
	v_addc_co_u32_e32 v17, vcc, 0, v7, vcc
	global_load_dword v22, v[16:17], off
	v_add_co_u32_e32 v16, vcc, 0x2df71000, v6
	s_nop 1
	v_addc_co_u32_e32 v17, vcc, 0, v7, vcc
	global_load_dword v23, v[16:17], off
	v_add_co_u32_e32 v16, vcc, 0x2db62000, v6
	s_nop 1
	v_addc_co_u32_e32 v17, vcc, 0, v7, vcc
	global_load_dword v24, v[16:17], off
	v_add_co_u32_e32 v16, vcc, 0x2df72000, v6
	s_nop 1
	v_addc_co_u32_e32 v17, vcc, 0, v7, vcc
	global_load_dword v25, v[16:17], off
	v_add_co_u32_e32 v16, vcc, 0x2db63000, v6
	s_nop 1
	v_addc_co_u32_e32 v17, vcc, 0, v7, vcc
	global_load_dword v26, v[16:17], off
	v_add_co_u32_e32 v16, vcc, 0x2df73000, v6
	s_nop 1
	v_addc_co_u32_e32 v17, vcc, 0, v7, vcc
	global_load_dword v27, v[16:17], off
	v_add_co_u32_e32 v16, vcc, 0x2db64000, v6
	s_nop 1
	v_addc_co_u32_e32 v17, vcc, 0, v7, vcc
	global_load_dword v28, v[16:17], off
	v_add_co_u32_e32 v16, vcc, 0x2df74000, v6
	s_nop 1
	v_addc_co_u32_e32 v17, vcc, 0, v7, vcc
	global_load_dword v29, v[16:17], off
	v_add_co_u32_e32 v16, vcc, 0x2db65000, v6
	s_nop 1
	v_addc_co_u32_e32 v17, vcc, 0, v7, vcc
	global_load_dword v30, v[16:17], off
	v_add_co_u32_e32 v16, vcc, 0x2df75000, v6
	s_nop 1
	v_addc_co_u32_e32 v17, vcc, 0, v7, vcc
	global_load_dword v31, v[16:17], off
	v_add_co_u32_e32 v16, vcc, 0x2db66000, v6
	s_nop 1
	v_addc_co_u32_e32 v17, vcc, 0, v7, vcc
	global_load_dword v32, v[16:17], off
	v_add_co_u32_e32 v16, vcc, 0x2df76000, v6
	s_nop 1
	v_addc_co_u32_e32 v17, vcc, 0, v7, vcc
	global_load_dword v33, v[16:17], off
	v_add_co_u32_e32 v16, vcc, 0x2db67000, v6
	s_nop 1
	v_addc_co_u32_e32 v17, vcc, 0, v7, vcc
	global_load_dword v34, v[16:17], off
	v_add_co_u32_e32 v16, vcc, 0x2df77000, v6
	s_nop 1
	v_addc_co_u32_e32 v17, vcc, 0, v7, vcc
	global_load_dword v35, v[16:17], off
	v_add_co_u32_e32 v16, vcc, 0x2db68000, v6
	s_nop 1
	v_addc_co_u32_e32 v17, vcc, 0, v7, vcc
	global_load_dword v36, v[16:17], off
	v_add_co_u32_e32 v16, vcc, 0x2df78000, v6
	s_nop 1
	v_addc_co_u32_e32 v17, vcc, 0, v7, vcc
	global_load_dword v37, v[16:17], off
	v_add_co_u32_e32 v16, vcc, 0x2db69000, v6
	s_nop 1
	v_addc_co_u32_e32 v17, vcc, 0, v7, vcc
	global_load_dword v38, v[16:17], off
	v_add_co_u32_e32 v16, vcc, 0x2df79000, v6
	s_nop 1
	v_addc_co_u32_e32 v17, vcc, 0, v7, vcc
	global_load_dword v39, v[16:17], off
	v_add_co_u32_e32 v16, vcc, 0x2db6a000, v6
	s_nop 1
	v_addc_co_u32_e32 v17, vcc, 0, v7, vcc
	global_load_dword v40, v[16:17], off
	v_add_co_u32_e32 v16, vcc, 0x2df7a000, v6
	s_nop 1
	v_addc_co_u32_e32 v17, vcc, 0, v7, vcc
	global_load_dword v41, v[16:17], off
	v_add_co_u32_e32 v16, vcc, 0x2db6b000, v6
	s_nop 1
	v_addc_co_u32_e32 v17, vcc, 0, v7, vcc
	global_load_dword v42, v[16:17], off
	v_add_co_u32_e32 v16, vcc, 0x2df7b000, v6
	s_nop 1
	v_addc_co_u32_e32 v17, vcc, 0, v7, vcc
	global_load_dword v43, v[16:17], off
	v_add_co_u32_e32 v16, vcc, 0x2db6c000, v6
	s_nop 1
	v_addc_co_u32_e32 v17, vcc, 0, v7, vcc
	global_load_dword v44, v[16:17], off
	v_add_co_u32_e32 v16, vcc, 0x2df7c000, v6
	s_nop 1
	v_addc_co_u32_e32 v17, vcc, 0, v7, vcc
	global_load_dword v45, v[16:17], off
	s_waitcnt vmcnt(25)
	v_mul_f32_e32 v13, 0x3fb8aa3b, v20
	v_exp_f32_e32 v13, v13
	s_nop 0
	v_mul_f32_e32 v9, v9, v13
	s_waitcnt vmcnt(24)
	v_pk_add_f32 v[8:9], v[8:9], v[20:21]
	s_waitcnt vmcnt(23)
	v_mul_f32_e32 v13, 0x3fb8aa3b, v22
	v_exp_f32_e32 v13, v13
	s_nop 0
	v_mul_f32_e32 v9, v9, v13
	s_waitcnt vmcnt(22)
	v_pk_add_f32 v[8:9], v[8:9], v[22:23]
	s_waitcnt vmcnt(21)
	v_mul_f32_e32 v13, 0x3fb8aa3b, v24
	v_exp_f32_e32 v13, v13
	s_nop 0
	v_mul_f32_e32 v9, v9, v13
	s_waitcnt vmcnt(20)
	v_pk_add_f32 v[8:9], v[8:9], v[24:25]
	s_waitcnt vmcnt(19)
	v_mul_f32_e32 v13, 0x3fb8aa3b, v26
	v_exp_f32_e32 v13, v13
	s_nop 0
	v_mul_f32_e32 v9, v9, v13
	s_waitcnt vmcnt(18)
	v_pk_add_f32 v[8:9], v[8:9], v[26:27]
	s_waitcnt vmcnt(17)
	v_mul_f32_e32 v13, 0x3fb8aa3b, v28
	v_exp_f32_e32 v13, v13
	s_nop 0
	v_mul_f32_e32 v9, v9, v13
	s_waitcnt vmcnt(16)
	v_pk_add_f32 v[8:9], v[8:9], v[28:29]
	s_waitcnt vmcnt(15)
	v_mul_f32_e32 v13, 0x3fb8aa3b, v30
	v_exp_f32_e32 v13, v13
	s_nop 0
	v_mul_f32_e32 v9, v9, v13
	s_waitcnt vmcnt(14)
	v_pk_add_f32 v[8:9], v[8:9], v[30:31]
	s_waitcnt vmcnt(13)
	v_mul_f32_e32 v13, 0x3fb8aa3b, v32
	v_exp_f32_e32 v13, v13
	s_nop 0
	v_mul_f32_e32 v9, v9, v13
	s_waitcnt vmcnt(12)
	v_pk_add_f32 v[8:9], v[8:9], v[32:33]
	s_waitcnt vmcnt(11)
	v_mul_f32_e32 v13, 0x3fb8aa3b, v34
	v_exp_f32_e32 v13, v13
	s_nop 0
	v_mul_f32_e32 v9, v9, v13
	s_waitcnt vmcnt(10)
	v_pk_add_f32 v[8:9], v[8:9], v[34:35]
	s_waitcnt vmcnt(9)
	v_mul_f32_e32 v13, 0x3fb8aa3b, v36
	v_exp_f32_e32 v13, v13
	s_nop 0
	v_mul_f32_e32 v9, v9, v13
	s_waitcnt vmcnt(8)
	v_pk_add_f32 v[8:9], v[8:9], v[36:37]
	s_waitcnt vmcnt(7)
	v_mul_f32_e32 v13, 0x3fb8aa3b, v38
	v_exp_f32_e32 v13, v13
	s_nop 0
	v_mul_f32_e32 v9, v9, v13
	s_waitcnt vmcnt(6)
	v_pk_add_f32 v[8:9], v[8:9], v[38:39]
	s_waitcnt vmcnt(5)
	v_mul_f32_e32 v13, 0x3fb8aa3b, v40
	v_exp_f32_e32 v13, v13
	s_nop 0
	v_mul_f32_e32 v9, v9, v13
	s_waitcnt vmcnt(4)
	v_pk_add_f32 v[8:9], v[8:9], v[40:41]
	s_waitcnt vmcnt(3)
	v_mul_f32_e32 v13, 0x3fb8aa3b, v42
	v_exp_f32_e32 v13, v13
	s_nop 0
	v_mul_f32_e32 v9, v9, v13
	s_waitcnt vmcnt(2)
	v_pk_add_f32 v[8:9], v[8:9], v[42:43]
	s_waitcnt vmcnt(1)
	v_mul_f32_e32 v13, 0x3fb8aa3b, v44
	v_exp_f32_e32 v13, v13
	s_nop 0
	v_mul_f32_e32 v9, v9, v13
	s_waitcnt vmcnt(0)
	v_pk_add_f32 v[8:9], v[8:9], v[44:45]
	s_cmp_eq_u32 s2, 0x41000
	s_cbranch_scc0 .LBB0_1127
	ds_write_b64 v11, v[8:9]
	v_mov_b32_e32 v8, 0
	s_waitcnt lgkmcnt(0)
	s_barrier
	s_and_saveexec_b64 s[2:3], s[38:39]
	s_cbranch_execz .LBB0_1132
	v_mov_b32_e32 v8, 0
	s_mov_b64 s[12:13], 0
	v_mov_b32_e32 v6, v12
	v_mov_b32_e32 v7, v10

; DEVI void lru_p2_phase(const Params& p, char* lds) {
;     ...
;     h = cin;
; #pragma unroll 13
;     for (int i = 0; i < 65; ++i) { const float Pc = AGP[base + (size_t)i * 1024], Bc = AGB[base + (size_t)i * 1024]; CAR[base + (size_t)i * 1024] = h; h = __expf(Pc) * h + Bc; }
.LBB0_1133:
	v_lshl_add_u64 v[6:7], v[4:5], 0, s[2:3]
	s_add_u32 s2, s2, 0xd000
	s_addc_u32 s3, s3, 0
	v_add_co_u32_e32 v16, vcc, 0x2db60000, v6
	s_nop 1
	v_addc_co_u32_e32 v17, vcc, 0, v7, vcc
	global_load_dword v20, v[16:17], off
	v_add_co_u32_e32 v16, vcc, 0x2df70000, v6
	s_nop 1
	v_addc_co_u32_e32 v17, vcc, 0, v7, vcc
	global_load_dword v21, v[16:17], off
	v_add_co_u32_e32 v16, vcc, 0x2db61000, v6
	s_nop 1
	v_addc_co_u32_e32 v17, vcc, 0, v7, vcc
	global_load_dword v22, v[16:17], off
	v_add_co_u32_e32 v16, vcc, 0x2df71000, v6
	s_nop 1
	v_addc_co_u32_e32 v17, vcc, 0, v7, vcc
	global_load_dword v23, v[16:17], off
	v_add_co_u32_e32 v16, vcc, 0x2db62000, v6
	s_nop 1
	v_addc_co_u32_e32 v17, vcc, 0, v7, vcc
	global_load_dword v24, v[16:17], off
	v_add_co_u32_e32 v16, vcc, 0x2df72000, v6
	s_nop 1
	v_addc_co_u32_e32 v17, vcc, 0, v7, vcc
	global_load_dword v25, v[16:17], off
	v_add_co_u32_e32 v16, vcc, 0x2db63000, v6
	s_nop 1
	v_addc_co_u32_e32 v17, vcc, 0, v7, vcc
	global_load_dword v26, v[16:17], off
	v_add_co_u32_e32 v16, vcc, 0x2df73000, v6
	s_nop 1
	v_addc_co_u32_e32 v17, vcc, 0, v7, vcc
	global_load_dword v27, v[16:17], off
	v_add_co_u32_e32 v16, vcc, 0x2db64000, v6
	s_nop 1
	v_addc_co_u32_e32 v17, vcc, 0, v7, vcc
	global_load_dword v28, v[16:17], off
	v_add_co_u32_e32 v16, vcc, 0x2df74000, v6
	s_nop 1
	v_addc_co_u32_e32 v17, vcc, 0, v7, vcc
	global_load_dword v29, v[16:17], off
	v_add_co_u32_e32 v16, vcc, 0x2db65000, v6
	s_nop 1
	v_addc_co_u32_e32 v17, vcc, 0, v7, vcc
	global_load_dword v30, v[16:17], off
	v_add_co_u32_e32 v16, vcc, 0x2df75000, v6
	s_nop 1
	v_addc_co_u32_e32 v17, vcc, 0, v7, vcc
	global_load_dword v31, v[16:17], off
	v_add_co_u32_e32 v16, vcc, 0x2db66000, v6
	s_nop 1
	v_addc_co_u32_e32 v17, vcc, 0, v7, vcc
	global_load_dword v32, v[16:17], off
	v_add_co_u32_e32 v16, vcc, 0x2df76000, v6
	s_nop 1
	v_addc_co_u32_e32 v17, vcc, 0, v7, vcc
	global_load_dword v33, v[16:17], off
	v_add_co_u32_e32 v16, vcc, 0x2db67000, v6
	s_nop 1
	v_addc_co_u32_e32 v17, vcc, 0, v7, vcc
	global_load_dword v34, v[16:17], off
	v_add_co_u32_e32 v16, vcc, 0x2df77000, v6
	s_nop 1
	v_addc_co_u32_e32 v17, vcc, 0, v7, vcc
	global_load_dword v35, v[16:17], off
	v_add_co_u32_e32 v16, vcc, 0x2db68000, v6
	s_nop 1
	v_addc_co_u32_e32 v17, vcc, 0, v7, vcc
	global_load_dword v36, v[16:17], off
	v_add_co_u32_e32 v16, vcc, 0x2df78000, v6
	s_nop 1
	v_addc_co_u32_e32 v17, vcc, 0, v7, vcc
	global_load_dword v37, v[16:17], off
	v_add_co_u32_e32 v16, vcc, 0x2db69000, v6
	s_nop 1
	v_addc_co_u32_e32 v17, vcc, 0, v7, vcc
	global_load_dword v38, v[16:17], off
	v_add_co_u32_e32 v16, vcc, 0x2df79000, v6
	s_nop 1
	v_addc_co_u32_e32 v17, vcc, 0, v7, vcc
	global_load_dword v39, v[16:17], off
	v_add_co_u32_e32 v16, vcc, 0x2db6a000, v6
	s_nop 1
	v_addc_co_u32_e32 v17, vcc, 0, v7, vcc
	global_load_dword v40, v[16:17], off
	v_add_co_u32_e32 v16, vcc, 0x2df7a000, v6
	s_nop 1
	v_addc_co_u32_e32 v17, vcc, 0, v7, vcc
	global_load_dword v41, v[16:17], off
	v_add_co_u32_e32 v16, vcc, 0x2db6b000, v6
	s_nop 1
	v_addc_co_u32_e32 v17, vcc, 0, v7, vcc
	global_load_dword v42, v[16:17], off
	v_add_co_u32_e32 v16, vcc, 0x2df7b000, v6
	s_nop 1
	v_addc_co_u32_e32 v17, vcc, 0, v7, vcc
	global_load_dword v43, v[16:17], off
	v_add_co_u32_e32 v16, vcc, 0x2db6c000, v6
	s_nop 1
	v_addc_co_u32_e32 v17, vcc, 0, v7, vcc
	global_load_dword v44, v[16:17], off
	v_add_co_u32_e32 v16, vcc, 0x2df7c000, v6
	s_nop 1
	v_addc_co_u32_e32 v17, vcc, 0, v7, vcc
	global_load_dword v45, v[16:17], off
	v_add_co_u32_e32 v16, vcc, 0x2e380000, v6
	s_nop 1
	v_addc_co_u32_e32 v17, vcc, 0, v7, vcc
	global_store_dword v[16:17], v8, off
	s_waitcnt vmcnt(26)
	v_mul_f32_e32 v13, 0x3fb8aa3b, v20
	v_exp_f32_e32 v13, v13
	s_waitcnt vmcnt(25)
	v_fmac_f32_e32 v21, v8, v13
	v_add_co_u32_e32 v16, vcc, 0x2e381000, v6
	s_nop 1
	v_addc_co_u32_e32 v17, vcc, 0, v7, vcc
	global_store_dword v[16:17], v21, off
	s_waitcnt vmcnt(25)
	v_mul_f32_e32 v13, 0x3fb8aa3b, v22
	v_exp_f32_e32 v13, v13
	s_waitcnt vmcnt(24)
	v_fmac_f32_e32 v23, v21, v13
	v_add_co_u32_e32 v16, vcc, 0x2e382000, v6
	s_nop 1
	v_addc_co_u32_e32 v17, vcc, 0, v7, vcc
	global_store_dword v[16:17], v23, off
	s_waitcnt vmcnt(24)
	v_mul_f32_e32 v13, 0x3fb8aa3b, v24
	v_exp_f32_e32 v13, v13
	s_waitcnt vmcnt(23)
	v_fmac_f32_e32 v25, v23, v13
	v_add_co_u32_e32 v16, vcc, 0x2e383000, v6
	s_nop 1
	v_addc_co_u32_e32 v17, vcc, 0, v7, vcc
	global_store_dword v[16:17], v25, off
	s_waitcnt vmcnt(23)
	v_mul_f32_e32 v13, 0x3fb8aa3b, v26
	v_exp_f32_e32 v13, v13
	s_waitcnt vmcnt(22)
	v_fmac_f32_e32 v27, v25, v13
	v_add_co_u32_e32 v16, vcc, 0x2e384000, v6
	s_nop 1
	v_addc_co_u32_e32 v17, vcc, 0, v7, vcc
	global_store_dword v[16:17], v27, off
	s_waitcnt vmcnt(22)
	v_mul_f32_e32 v13, 0x3fb8aa3b, v28
	v_exp_f32_e32 v13, v13
	s_waitcnt vmcnt(21)
	v_fmac_f32_e32 v29, v27, v13
	v_add_co_u32_e32 v16, vcc, 0x2e385000, v6
	s_nop 1
	v_addc_co_u32_e32 v17, vcc, 0, v7, vcc
	global_store_dword v[16:17], v29, off
	s_waitcnt vmcnt(21)
	v_mul_f32_e32 v13, 0x3fb8aa3b, v30
	v_exp_f32_e32 v13, v13
	s_waitcnt vmcnt(20)
	v_fmac_f32_e32 v31, v29, v13
	v_add_co_u32_e32 v16, vcc, 0x2e386000, v6
	s_nop 1
	v_addc_co_u32_e32 v17, vcc, 0, v7, vcc
	global_store_dword v[16:17], v31, off
	s_waitcnt vmcnt(20)
	v_mul_f32_e32 v13, 0x3fb8aa3b, v32
	v_exp_f32_e32 v13, v13
	s_waitcnt vmcnt(19)
	v_fmac_f32_e32 v33, v31, v13
	v_add_co_u32_e32 v16, vcc, 0x2e387000, v6
	s_nop 1
	v_addc_co_u32_e32 v17, vcc, 0, v7, vcc
	global_store_dword v[16:17], v33, off
	s_waitcnt vmcnt(19)
	v_mul_f32_e32 v13, 0x3fb8aa3b, v34
	v_exp_f32_e32 v13, v13
	s_waitcnt vmcnt(18)
	v_fmac_f32_e32 v35, v33, v13
	v_add_co_u32_e32 v16, vcc, 0x2e388000, v6
	s_nop 1
	v_addc_co_u32_e32 v17, vcc, 0, v7, vcc
	global_store_dword v[16:17], v35, off
	s_waitcnt vmcnt(18)
	v_mul_f32_e32 v13, 0x3fb8aa3b, v36
	v_exp_f32_e32 v13, v13
	s_waitcnt vmcnt(17)
	v_fmac_f32_e32 v37, v35, v13
	v_add_co_u32_e32 v16, vcc, 0x2e389000, v6
	s_nop 1
	v_addc_co_u32_e32 v17, vcc, 0, v7, vcc
	global_store_dword v[16:17], v37, off
	s_waitcnt vmcnt(17)
	v_mul_f32_e32 v13, 0x3fb8aa3b, v38
	v_exp_f32_e32 v13, v13
	s_waitcnt vmcnt(16)
	v_fmac_f32_e32 v39, v37, v13
	v_add_co_u32_e32 v16, vcc, 0x2e38a000, v6
	s_nop 1
	v_addc_co_u32_e32 v17, vcc, 0, v7, vcc
	global_store_dword v[16:17], v39, off
	s_waitcnt vmcnt(16)
	v_mul_f32_e32 v13, 0x3fb8aa3b, v40
	v_exp_f32_e32 v13, v13
	s_waitcnt vmcnt(15)
	v_fmac_f32_e32 v41, v39, v13
	v_add_co_u32_e32 v16, vcc, 0x2e38b000, v6
	s_nop 1
	v_addc_co_u32_e32 v17, vcc, 0, v7, vcc
	global_store_dword v[16:17], v41, off
	s_waitcnt vmcnt(15)
	v_mul_f32_e32 v13, 0x3fb8aa3b, v42
	v_exp_f32_e32 v13, v13
	s_waitcnt vmcnt(14)
	v_fmac_f32_e32 v43, v41, v13
	v_add_co_u32_e32 v16, vcc, 0x2e38c000, v6
	s_nop 1
	v_addc_co_u32_e32 v17, vcc, 0, v7, vcc
	global_store_dword v[16:17], v43, off
	s_waitcnt vmcnt(14)
	v_mul_f32_e32 v13, 0x3fb8aa3b, v44
	v_exp_f32_e32 v13, v13
	s_waitcnt vmcnt(13)
	v_fmac_f32_e32 v45, v43, v13
	v_mov_b32_e32 v8, v45
	s_cmp_eq_u32 s2, 0x41000
	s_cbranch_scc0 .LBB0_1133
; DEVI int lbid() { int t = blockIdx.x; asm volatile("" : "+s"(t)); return t; }
; DEVI int lgdim() { int t = gridDim.x; asm volatile("" : "+s"(t)); return t; }
; DEVI void lru_p2_phase(const Params& p, char* lds) {
;     ...
;   for (int it = lbid(); it < 32; it += lgdim()) {
	s_mov_b32 s1, s50
	s_add_i32 s0, s1, s0
	s_cmp_gt_i32 s0, 31
	s_cbranch_scc0 .LBB0_1126

; DEVI void s5_carry_phase(const Params& p, char* lds) {
;     ...
; #pragma unroll 10
;     for (int i = 0; i < 130; ++i) {
;       const int pos = w * 130 + i;
;       const int c = dir == 0 ? pos : (pos < 16 ? 15 - pos : 1055 - pos);
;       const size_t o = base + (size_t)c * 256;
;       const float lr = SLOC[o + nre], li = SLOC[o + nim];
;       const float nr = a16.x * sr - a16.y * si + lr, ni = a16.x * si + a16.y * sr + li; sr = nr; si = ni;
;       const float qr = a16.x * pr - a16.y * pi, qi = a16.x * pi + a16.y * pr; pr = qr; pi = qi;
;     }
.LBB0_2115:
	v_add_u32_e32 v60, -9, v21
	v_cmp_lt_i32_e64 s[40:41], 15, v60
	s_nop 1
	v_cndmask_b32_e64 v61, 15, v235, s[40:41]
	v_add3_u32 v61, v3, v61, s0
	v_add_u32_e32 v61, 0xffffff7e, v61
	v_cndmask_b32_e64 v62, v61, v60, s[38:39]
	v_ashrrev_i32_e32 v63, 31, v62
	v_lshl_add_u64 v[62:63], s[24:25], 0, v[62:63]
	v_lshlrev_b64 v[62:63], 10, v[62:63]
	v_lshl_add_u64 v[62:63], v[10:11], 0, v[62:63]
	global_load_dword v40, v[62:63], off
	global_load_dword v41, v[62:63], off offset:256
	v_add_u32_e32 v60, -8, v21
	v_cmp_lt_i32_e64 s[40:41], 15, v60
	s_nop 1
	v_cndmask_b32_e64 v61, 15, v235, s[40:41]
	v_add3_u32 v61, v3, v61, s0
	v_add_u32_e32 v61, 0xffffff7d, v61
	v_cndmask_b32_e64 v62, v61, v60, s[38:39]
	v_ashrrev_i32_e32 v63, 31, v62
	v_lshl_add_u64 v[62:63], s[24:25], 0, v[62:63]
	v_lshlrev_b64 v[62:63], 10, v[62:63]
	v_lshl_add_u64 v[62:63], v[10:11], 0, v[62:63]
	global_load_dword v42, v[62:63], off
	global_load_dword v43, v[62:63], off offset:256
	v_add_u32_e32 v60, -7, v21
	v_cmp_lt_i32_e64 s[40:41], 15, v60
	s_nop 1
	v_cndmask_b32_e64 v61, 15, v235, s[40:41]
	v_add3_u32 v61, v3, v61, s0
	v_add_u32_e32 v61, 0xffffff7c, v61
	v_cndmask_b32_e64 v62, v61, v60, s[38:39]
	v_ashrrev_i32_e32 v63, 31, v62
	v_lshl_add_u64 v[62:63], s[24:25], 0, v[62:63]
	v_lshlrev_b64 v[62:63], 10, v[62:63]
	v_lshl_add_u64 v[62:63], v[10:11], 0, v[62:63]
	global_load_dword v44, v[62:63], off
	global_load_dword v45, v[62:63], off offset:256
	v_add_u32_e32 v60, -6, v21
	v_cmp_lt_i32_e64 s[40:41], 15, v60
	s_nop 1
	v_cndmask_b32_e64 v61, 15, v235, s[40:41]
	v_add3_u32 v61, v3, v61, s0
	v_add_u32_e32 v61, 0xffffff7b, v61
	v_cndmask_b32_e64 v62, v61, v60, s[38:39]
	v_ashrrev_i32_e32 v63, 31, v62
	v_lshl_add_u64 v[62:63], s[24:25], 0, v[62:63]
	v_lshlrev_b64 v[62:63], 10, v[62:63]
	v_lshl_add_u64 v[62:63], v[10:11], 0, v[62:63]
	global_load_dword v46, v[62:63], off
	global_load_dword v47, v[62:63], off offset:256
	v_add_u32_e32 v60, -5, v21
	v_cmp_lt_i32_e64 s[40:41], 15, v60
	s_nop 1
	v_cndmask_b32_e64 v61, 15, v235, s[40:41]
	v_add3_u32 v61, v3, v61, s0
	v_add_u32_e32 v61, 0xffffff7a, v61
	v_cndmask_b32_e64 v62, v61, v60, s[38:39]
	v_ashrrev_i32_e32 v63, 31, v62
	v_lshl_add_u64 v[62:63], s[24:25], 0, v[62:63]
	v_lshlrev_b64 v[62:63], 10, v[62:63]
	v_lshl_add_u64 v[62:63], v[10:11], 0, v[62:63]
	global_load_dword v48, v[62:63], off
	global_load_dword v49, v[62:63], off offset:256
	v_add_u32_e32 v60, -4, v21
	v_cmp_lt_i32_e64 s[40:41], 15, v60
	s_nop 1
	v_cndmask_b32_e64 v61, 15, v235, s[40:41]
	v_add3_u32 v61, v3, v61, s0
	v_add_u32_e32 v61, 0xffffff79, v61
	v_cndmask_b32_e64 v62, v61, v60, s[38:39]
	v_ashrrev_i32_e32 v63, 31, v62
	v_lshl_add_u64 v[62:63], s[24:25], 0, v[62:63]
	v_lshlrev_b64 v[62:63], 10, v[62:63]
	v_lshl_add_u64 v[62:63], v[10:11], 0, v[62:63]
	global_load_dword v50, v[62:63], off
	global_load_dword v51, v[62:63], off offset:256
	v_add_u32_e32 v60, -3, v21
	v_cmp_lt_i32_e64 s[40:41], 15, v60
	s_nop 1
	v_cndmask_b32_e64 v61, 15, v235, s[40:41]
	v_add3_u32 v61, v3, v61, s0
	v_add_u32_e32 v61, 0xffffff78, v61
	v_cndmask_b32_e64 v62, v61, v60, s[38:39]
	v_ashrrev_i32_e32 v63, 31, v62
	v_lshl_add_u64 v[62:63], s[24:25], 0, v[62:63]
	v_lshlrev_b64 v[62:63], 10, v[62:63]
	v_lshl_add_u64 v[62:63], v[10:11], 0, v[62:63]
	global_load_dword v52, v[62:63], off
	global_load_dword v53, v[62:63], off offset:256
	v_add_u32_e32 v60, -2, v21
	v_cmp_lt_i32_e64 s[40:41], 15, v60
	s_nop 1
	v_cndmask_b32_e64 v61, 15, v235, s[40:41]
	v_add3_u32 v61, v3, v61, s0
	v_add_u32_e32 v61, 0xffffff77, v61
	v_cndmask_b32_e64 v62, v61, v60, s[38:39]
	v_ashrrev_i32_e32 v63, 31, v62
	v_lshl_add_u64 v[62:63], s[24:25], 0, v[62:63]
	v_lshlrev_b64 v[62:63], 10, v[62:63]
	v_lshl_add_u64 v[62:63], v[10:11], 0, v[62:63]
	global_load_dword v54, v[62:63], off
	global_load_dword v55, v[62:63], off offset:256
	v_add_u32_e32 v60, -1, v21
	v_cmp_lt_i32_e64 s[40:41], 15, v60
	s_nop 1
	v_cndmask_b32_e64 v61, 15, v235, s[40:41]
	v_add3_u32 v61, v3, v61, s0
	v_add_u32_e32 v61, 0xffffff76, v61
	v_cndmask_b32_e64 v62, v61, v60, s[38:39]
	v_ashrrev_i32_e32 v63, 31, v62
	v_lshl_add_u64 v[62:63], s[24:25], 0, v[62:63]
	v_lshlrev_b64 v[62:63], 10, v[62:63]
	v_lshl_add_u64 v[62:63], v[10:11], 0, v[62:63]
	global_load_dword v56, v[62:63], off
	global_load_dword v57, v[62:63], off offset:256
	v_mov_b32_e32 v60, v21
	v_cmp_lt_i32_e64 s[40:41], 15, v60
	s_nop 1
	v_cndmask_b32_e64 v61, 15, v235, s[40:41]
	v_add3_u32 v61, v3, v61, s0
	v_add_u32_e32 v61, 0xffffff75, v61
	v_cndmask_b32_e64 v62, v61, v60, s[38:39]
	v_ashrrev_i32_e32 v63, 31, v62
	v_lshl_add_u64 v[62:63], s[24:25], 0, v[62:63]
	v_lshlrev_b64 v[62:63], 10, v[62:63]
	v_lshl_add_u64 v[62:63], v[10:11], 0, v[62:63]
	global_load_dword v58, v[62:63], off
	global_load_dword v59, v[62:63], off offset:256
	v_add_u32_e32 v13, -9, v21
	v_cmp_lt_i32_e64 s[40:41], 15, v13
	v_pk_mul_f32 v[16:17], v[8:9], v[16:17] op_sel_hi:[1,0]
	s_nop 0
	v_cndmask_b32_e64 v15, 15, v235, s[40:41]
	v_add3_u32 v15, v3, v15, s0
	v_add_u32_e32 v15, 0xffffff7e, v15
	v_cndmask_b32_e64 v22, v15, v13, s[38:39]
	v_ashrrev_i32_e32 v23, 31, v22
	v_lshl_add_u64 v[22:23], s[24:25], 0, v[22:23]
	v_lshlrev_b64 v[22:23], 10, v[22:23]
	v_lshl_add_u64 v[22:23], v[10:11], 0, v[22:23]
	v_pk_mul_f32 v[22:23], v[8:9], v[0:1] op_sel_hi:[1,0]
	v_add_u32_e32 v0, -8, v21
	v_cmp_lt_i32_e64 s[40:41], 15, v0
	v_pk_fma_f32 v[26:27], v[4:5], v[14:15], v[22:23] neg_lo:[0,0,1] neg_hi:[0,0,1]
	v_pk_fma_f32 v[14:15], v[4:5], v[14:15], v[22:23] op_sel_hi:[1,0,1]
	v_cndmask_b32_e64 v22, 15, v235, s[40:41]
	v_add3_u32 v22, v3, v22, s0
	v_add_u32_e32 v22, 0xffffff7d, v22
	v_cndmask_b32_e64 v22, v22, v0, s[38:39]
	v_ashrrev_i32_e32 v23, 31, v22
	v_lshl_add_u64 v[22:23], s[24:25], 0, v[22:23]
	v_lshlrev_b64 v[22:23], 10, v[22:23]
	v_mov_b32_e32 v27, v15
	v_lshl_add_u64 v[22:23], v[10:11], 0, v[22:23]
	v_pk_mul_f32 v[12:13], v[4:5], v[12:13] op_sel_hi:[1,0]
	s_waitcnt vmcnt(18)
; DEVI void s5_carry_phase(const Params& p, char* lds) {
;     ...
;     for (int i = 0; i < 130; ++i) {
;       const int pos = w * 130 + i;
;       const int c = dir == 0 ? pos : (pos < 16 ? 15 - pos : 1055 - pos);
;       const size_t o = base + (size_t)c * 256;
;       const float lr = SLOC[o + nre], li = SLOC[o + nim];
;       const float nr = a16.x * sr - a16.y * si + lr, ni = a16.x * si + a16.y * sr + li; sr = nr; si = ni;
;       const float qr = a16.x * pr - a16.y * pi, qi = a16.x * pi + a16.y * pr; pr = qr; pi = qi;
;     }
	v_pk_add_f32 v[14:15], v[26:27], v[40:41]
	v_pk_mul_f32 v[22:23], v[8:9], v[14:15] op_sel:[0,1]
	v_add_f32_e32 v0, v16, v12
	v_pk_fma_f32 v[26:27], v[4:5], v[14:15], v[22:23] neg_lo:[0,0,1] neg_hi:[0,0,1]
	v_pk_fma_f32 v[14:15], v[4:5], v[14:15], v[22:23] op_sel_hi:[1,0,1]
	v_pk_mul_f32 v[22:23], v[4:5], v[0:1] op_sel_hi:[1,0]
	v_sub_f32_e32 v0, v17, v13
	v_pk_mul_f32 v[12:13], v[8:9], v[0:1] op_sel_hi:[1,0]
	v_add_u32_e32 v0, -7, v21
	v_cmp_lt_i32_e64 s[40:41], 15, v0
	v_mov_b32_e32 v27, v15
	s_waitcnt vmcnt(16)
	v_pk_add_f32 v[14:15], v[26:27], v[42:43]
	v_cndmask_b32_e64 v16, 15, v235, s[40:41]
	v_add3_u32 v16, v3, v16, s0
	v_add_u32_e32 v16, 0xffffff7c, v16
	v_cndmask_b32_e64 v16, v16, v0, s[38:39]
	v_ashrrev_i32_e32 v17, 31, v16
	v_lshl_add_u64 v[16:17], s[24:25], 0, v[16:17]
	v_lshlrev_b64 v[16:17], 10, v[16:17]
	v_lshl_add_u64 v[16:17], v[10:11], 0, v[16:17]
	v_pk_mul_f32 v[16:17], v[8:9], v[14:15] op_sel:[0,1]
	v_add_f32_e32 v0, v12, v22
	v_pk_fma_f32 v[26:27], v[4:5], v[14:15], v[16:17] neg_lo:[0,0,1] neg_hi:[0,0,1]
	v_pk_fma_f32 v[14:15], v[4:5], v[14:15], v[16:17] op_sel_hi:[1,0,1]
	v_pk_mul_f32 v[16:17], v[4:5], v[0:1] op_sel_hi:[1,0]
	v_sub_f32_e32 v0, v13, v23
	v_pk_mul_f32 v[12:13], v[8:9], v[0:1] op_sel_hi:[1,0]
	v_add_u32_e32 v0, -6, v21
	v_cmp_lt_i32_e64 s[40:41], 15, v0
	v_mov_b32_e32 v27, v15
	s_waitcnt vmcnt(14)
	v_pk_add_f32 v[14:15], v[26:27], v[44:45]
	v_cndmask_b32_e64 v22, 15, v235, s[40:41]
	v_add3_u32 v22, v3, v22, s0
	v_add_u32_e32 v22, 0xffffff7b, v22
	v_cndmask_b32_e64 v22, v22, v0, s[38:39]
	v_ashrrev_i32_e32 v23, 31, v22
	v_lshl_add_u64 v[22:23], s[24:25], 0, v[22:23]
	v_lshlrev_b64 v[22:23], 10, v[22:23]
	v_lshl_add_u64 v[22:23], v[10:11], 0, v[22:23]
	v_pk_mul_f32 v[22:23], v[8:9], v[14:15] op_sel:[0,1]
	v_add_f32_e32 v0, v12, v16
	v_pk_fma_f32 v[26:27], v[4:5], v[14:15], v[22:23] neg_lo:[0,0,1] neg_hi:[0,0,1]
	v_pk_fma_f32 v[14:15], v[4:5], v[14:15], v[22:23] op_sel_hi:[1,0,1]
	v_pk_mul_f32 v[22:23], v[4:5], v[0:1] op_sel_hi:[1,0]
	v_sub_f32_e32 v0, v13, v17
	v_pk_mul_f32 v[12:13], v[8:9], v[0:1] op_sel_hi:[1,0]
	v_add_u32_e32 v0, -5, v21
	v_cmp_lt_i32_e64 s[40:41], 15, v0
	v_mov_b32_e32 v27, v15
	s_waitcnt vmcnt(12)
	v_pk_add_f32 v[14:15], v[26:27], v[46:47]
	v_cndmask_b32_e64 v16, 15, v235, s[40:41]
	v_add3_u32 v16, v3, v16, s0
	v_add_u32_e32 v16, 0xffffff7a, v16
	v_cndmask_b32_e64 v16, v16, v0, s[38:39]
	v_ashrrev_i32_e32 v17, 31, v16
	v_lshl_add_u64 v[16:17], s[24:25], 0, v[16:17]
	v_lshlrev_b64 v[16:17], 10, v[16:17]
	v_lshl_add_u64 v[16:17], v[10:11], 0, v[16:17]
	v_pk_mul_f32 v[16:17], v[8:9], v[14:15] op_sel:[0,1]
	v_add_f32_e32 v0, v12, v22
	v_pk_fma_f32 v[26:27], v[4:5], v[14:15], v[16:17] neg_lo:[0,0,1] neg_hi:[0,0,1]
	v_pk_fma_f32 v[14:15], v[4:5], v[14:15], v[16:17] op_sel_hi:[1,0,1]
	v_pk_mul_f32 v[16:17], v[4:5], v[0:1] op_sel_hi:[1,0]
	v_sub_f32_e32 v0, v13, v23
	v_pk_mul_f32 v[12:13], v[8:9], v[0:1] op_sel_hi:[1,0]
	v_add_u32_e32 v0, -4, v21
	v_cmp_lt_i32_e64 s[40:41], 15, v0
	v_mov_b32_e32 v27, v15
	s_waitcnt vmcnt(10)
	v_pk_add_f32 v[14:15], v[26:27], v[48:49]
	v_cndmask_b32_e64 v22, 15, v235, s[40:41]
	v_add3_u32 v22, v3, v22, s0
	v_add_u32_e32 v22, 0xffffff79, v22
	v_cndmask_b32_e64 v22, v22, v0, s[38:39]
	v_ashrrev_i32_e32 v23, 31, v22
	v_lshl_add_u64 v[22:23], s[24:25], 0, v[22:23]
	v_lshlrev_b64 v[22:23], 10, v[22:23]
	v_lshl_add_u64 v[22:23], v[10:11], 0, v[22:23]
	v_pk_mul_f32 v[22:23], v[8:9], v[14:15] op_sel:[0,1]
	v_add_f32_e32 v0, v12, v16
	v_pk_fma_f32 v[26:27], v[4:5], v[14:15], v[22:23] neg_lo:[0,0,1] neg_hi:[0,0,1]
	v_pk_fma_f32 v[14:15], v[4:5], v[14:15], v[22:23] op_sel_hi:[1,0,1]
	v_pk_mul_f32 v[22:23], v[4:5], v[0:1] op_sel_hi:[1,0]
	v_sub_f32_e32 v0, v13, v17
	v_pk_mul_f32 v[12:13], v[8:9], v[0:1] op_sel_hi:[1,0]
	v_add_u32_e32 v0, -3, v21
	v_cmp_lt_i32_e64 s[40:41], 15, v0
	v_mov_b32_e32 v27, v15
	s_waitcnt vmcnt(8)
; DEVI void s5_carry_phase(const Params& p, char* lds) {
;     ...
;     for (int i = 0; i < 130; ++i) {
;       const int pos = w * 130 + i;
;       const int c = dir == 0 ? pos : (pos < 16 ? 15 - pos : 1055 - pos);
;       const size_t o = base + (size_t)c * 256;
;       const float lr = SLOC[o + nre], li = SLOC[o + nim];
;       const float nr = a16.x * sr - a16.y * si + lr, ni = a16.x * si + a16.y * sr + li; sr = nr; si = ni;
;       const float qr = a16.x * pr - a16.y * pi, qi = a16.x * pi + a16.y * pr; pr = qr; pi = qi;
;     }
;     seg[w * 64 + pp] = make_float2(sr, si);
;     __syncthreads();
;     float cr = 0.f, ci = 0.f;
;     for (int v = 0; v < w; ++v) { const float2 e = seg[v * 64 + pp]; const float nr = pr * cr - pi * ci + e.x, ni = pr * ci + pi * cr + e.y; cr = nr; ci = ni; }
	v_pk_add_f32 v[14:15], v[26:27], v[50:51]
	v_cndmask_b32_e64 v16, 15, v235, s[40:41]
	v_add3_u32 v16, v3, v16, s0
	v_add_u32_e32 v16, 0xffffff78, v16
	v_cndmask_b32_e64 v16, v16, v0, s[38:39]
	v_ashrrev_i32_e32 v17, 31, v16
	v_lshl_add_u64 v[16:17], s[24:25], 0, v[16:17]
	v_lshlrev_b64 v[16:17], 10, v[16:17]
	v_lshl_add_u64 v[16:17], v[10:11], 0, v[16:17]
	v_pk_mul_f32 v[16:17], v[8:9], v[14:15] op_sel:[0,1]
	v_add_f32_e32 v0, v12, v22
	v_pk_fma_f32 v[26:27], v[4:5], v[14:15], v[16:17] neg_lo:[0,0,1] neg_hi:[0,0,1]
	v_pk_fma_f32 v[14:15], v[4:5], v[14:15], v[16:17] op_sel_hi:[1,0,1]
	v_pk_mul_f32 v[16:17], v[4:5], v[0:1] op_sel_hi:[1,0]
	v_sub_f32_e32 v0, v13, v23
	v_pk_mul_f32 v[12:13], v[8:9], v[0:1] op_sel_hi:[1,0]
	v_add_u32_e32 v0, -2, v21
	v_cmp_lt_i32_e64 s[40:41], 15, v0
	v_mov_b32_e32 v27, v15
	s_waitcnt vmcnt(6)
	v_pk_add_f32 v[14:15], v[26:27], v[52:53]
	v_cndmask_b32_e64 v22, 15, v235, s[40:41]
	v_add3_u32 v22, v3, v22, s0
	v_add_u32_e32 v22, 0xffffff77, v22
	v_cndmask_b32_e64 v22, v22, v0, s[38:39]
	v_ashrrev_i32_e32 v23, 31, v22
	v_lshl_add_u64 v[22:23], s[24:25], 0, v[22:23]
	v_lshlrev_b64 v[22:23], 10, v[22:23]
	v_lshl_add_u64 v[22:23], v[10:11], 0, v[22:23]
	v_pk_mul_f32 v[22:23], v[8:9], v[14:15] op_sel:[0,1]
	v_add_f32_e32 v0, v12, v16
	v_pk_fma_f32 v[26:27], v[4:5], v[14:15], v[22:23] neg_lo:[0,0,1] neg_hi:[0,0,1]
	v_pk_fma_f32 v[14:15], v[4:5], v[14:15], v[22:23] op_sel_hi:[1,0,1]
	v_pk_mul_f32 v[22:23], v[4:5], v[0:1] op_sel_hi:[1,0]
	v_sub_f32_e32 v0, v13, v17
	v_pk_mul_f32 v[12:13], v[8:9], v[0:1] op_sel_hi:[1,0]
	v_add_u32_e32 v0, -1, v21
	v_cmp_lt_i32_e64 s[40:41], 15, v0
	v_mov_b32_e32 v27, v15
	s_waitcnt vmcnt(4)
	v_pk_add_f32 v[14:15], v[26:27], v[54:55]
	v_cndmask_b32_e64 v16, 15, v235, s[40:41]
	v_add3_u32 v16, v3, v16, s0
	v_add_u32_e32 v16, 0xffffff76, v16
	v_cndmask_b32_e64 v16, v16, v0, s[38:39]
	v_ashrrev_i32_e32 v17, 31, v16
	v_lshl_add_u64 v[16:17], s[24:25], 0, v[16:17]
	v_lshlrev_b64 v[16:17], 10, v[16:17]
	v_lshl_add_u64 v[16:17], v[10:11], 0, v[16:17]
	v_pk_mul_f32 v[16:17], v[8:9], v[14:15] op_sel:[0,1]
	v_add_f32_e32 v0, v12, v22
	v_pk_fma_f32 v[26:27], v[4:5], v[14:15], v[16:17] neg_lo:[0,0,1] neg_hi:[0,0,1]
	v_pk_fma_f32 v[14:15], v[4:5], v[14:15], v[16:17] op_sel_hi:[1,0,1]
	v_pk_mul_f32 v[16:17], v[4:5], v[0:1] op_sel_hi:[1,0]
	v_sub_f32_e32 v0, v13, v23
	v_cmp_lt_i32_e64 s[40:41], 15, v21
	v_pk_mul_f32 v[12:13], v[8:9], v[0:1] op_sel_hi:[1,0]
	v_mov_b32_e32 v27, v15
	v_cndmask_b32_e64 v0, 15, v235, s[40:41]
	v_add3_u32 v0, v3, v0, s0
	v_add_u32_e32 v0, 0xffffff75, v0
	v_cndmask_b32_e64 v22, v0, v21, s[38:39]
	v_ashrrev_i32_e32 v23, 31, v22
	v_lshl_add_u64 v[22:23], s[24:25], 0, v[22:23]
	v_lshlrev_b64 v[22:23], 10, v[22:23]
	v_lshl_add_u64 v[22:23], v[10:11], 0, v[22:23]
	v_add_f32_e32 v0, v12, v16
	s_add_i32 s0, s0, -10
	v_add_u32_e32 v21, 10, v21
	s_cmp_eq_u32 s0, 0
	s_waitcnt vmcnt(2)
	v_pk_add_f32 v[14:15], v[26:27], v[56:57]
	v_pk_mul_f32 v[22:23], v[8:9], v[14:15] op_sel:[0,1]
	s_nop 0
	v_pk_fma_f32 v[26:27], v[4:5], v[14:15], v[22:23] neg_lo:[0,0,1] neg_hi:[0,0,1]
	v_pk_fma_f32 v[14:15], v[4:5], v[14:15], v[22:23] op_sel_hi:[1,0,1]
	v_pk_mul_f32 v[22:23], v[4:5], v[0:1] op_sel_hi:[1,0]
	v_mov_b32_e32 v27, v15
	v_sub_f32_e32 v0, v13, v17
	v_pk_fma_f32 v[16:17], v[8:9], v[0:1], v[22:23] op_sel_hi:[1,0,1] neg_lo:[0,0,1] neg_hi:[0,0,1]
	v_pk_fma_f32 v[12:13], v[8:9], v[0:1], v[22:23] op_sel_hi:[1,0,1]
	v_mov_b32_e32 v16, v17
	s_waitcnt vmcnt(0)
	v_pk_add_f32 v[14:15], v[26:27], v[58:59]
	s_nop 0
	v_mov_b32_e32 v0, v15
	s_cbranch_scc0 .LBB0_2115
	v_mov_b32_e32 v0, v1
	v_mov_b64_e32 v[10:11], v[0:1]
	ds_write_b64 v19, v[14:15]
	s_waitcnt lgkmcnt(0)
	s_barrier
	s_and_saveexec_b64 s[2:3], vcc
	s_cbranch_execz .LBB0_2120
	v_mov_b32_e32 v10, 0
	v_mov_b32_e32 v16, v17
	v_mov_b32_e32 v13, v12
	s_mov_b64 s[22:23], 0
	v_mov_b32_e32 v0, v20
	v_mov_b32_e32 v14, v7
	v_mov_b32_e32 v11, v10

; DEVI void s5_carry_phase(const Params& p, char* lds) {
;     ...
; #pragma unroll 10
;     for (int i = 0; i < 130; ++i) {
;       const int pos = w * 130 + i;
;       const int c = dir == 0 ? pos : (pos < 16 ? 15 - pos : 1055 - pos);
;       const size_t o = base + (size_t)c * 256;
;       const float lr = SLOC[o + nre], li = SLOC[o + nim];
.LBB0_2121:
	v_add_u32_e32 v60, -9, v12
	v_cmp_lt_i32_e64 s[40:41], 15, v60
	s_nop 1
	v_cndmask_b32_e64 v61, 15, v235, s[40:41]
	v_add3_u32 v61, v3, v61, s0
	v_add_u32_e32 v61, 0xffffff7e, v61
	v_cndmask_b32_e64 v62, v61, v60, s[38:39]
	v_ashrrev_i32_e32 v63, 31, v62
	v_lshl_add_u64 v[62:63], s[24:25], 0, v[62:63]
	v_lshlrev_b64 v[62:63], 8, v[62:63]
	v_or_b32_e32 v60, v62, v6
	v_mov_b32_e32 v61, v63
	v_or_b32_e32 v62, v62, v0
	v_lshl_add_u64 v[60:61], v[60:61], 2, s[12:13]
	v_lshl_add_u64 v[62:63], v[62:63], 2, s[12:13]
	global_load_dword v40, v[60:61], off
	global_load_dword v41, v[62:63], off
	v_add_u32_e32 v60, -8, v12
	v_cmp_lt_i32_e64 s[40:41], 15, v60
	s_nop 1
	v_cndmask_b32_e64 v61, 15, v235, s[40:41]
	v_add3_u32 v61, v3, v61, s0
	v_add_u32_e32 v61, 0xffffff7d, v61
	v_cndmask_b32_e64 v62, v61, v60, s[38:39]
	v_ashrrev_i32_e32 v63, 31, v62
	v_lshl_add_u64 v[62:63], s[24:25], 0, v[62:63]
	v_lshlrev_b64 v[62:63], 8, v[62:63]
	v_or_b32_e32 v60, v62, v6
	v_mov_b32_e32 v61, v63
	v_or_b32_e32 v62, v62, v0
	v_lshl_add_u64 v[60:61], v[60:61], 2, s[12:13]
	v_lshl_add_u64 v[62:63], v[62:63], 2, s[12:13]
	global_load_dword v42, v[60:61], off
	global_load_dword v43, v[62:63], off
	v_add_u32_e32 v60, -7, v12
	v_cmp_lt_i32_e64 s[40:41], 15, v60
	s_nop 1
	v_cndmask_b32_e64 v61, 15, v235, s[40:41]
	v_add3_u32 v61, v3, v61, s0
	v_add_u32_e32 v61, 0xffffff7c, v61
	v_cndmask_b32_e64 v62, v61, v60, s[38:39]
	v_ashrrev_i32_e32 v63, 31, v62
	v_lshl_add_u64 v[62:63], s[24:25], 0, v[62:63]
	v_lshlrev_b64 v[62:63], 8, v[62:63]
	v_or_b32_e32 v60, v62, v6
	v_mov_b32_e32 v61, v63
	v_or_b32_e32 v62, v62, v0
	v_lshl_add_u64 v[60:61], v[60:61], 2, s[12:13]
	v_lshl_add_u64 v[62:63], v[62:63], 2, s[12:13]
	global_load_dword v44, v[60:61], off
	global_load_dword v45, v[62:63], off
	v_add_u32_e32 v60, -6, v12
	v_cmp_lt_i32_e64 s[40:41], 15, v60
	s_nop 1
	v_cndmask_b32_e64 v61, 15, v235, s[40:41]
	v_add3_u32 v61, v3, v61, s0
	v_add_u32_e32 v61, 0xffffff7b, v61
	v_cndmask_b32_e64 v62, v61, v60, s[38:39]
	v_ashrrev_i32_e32 v63, 31, v62
	v_lshl_add_u64 v[62:63], s[24:25], 0, v[62:63]
	v_lshlrev_b64 v[62:63], 8, v[62:63]
	v_or_b32_e32 v60, v62, v6
	v_mov_b32_e32 v61, v63
	v_or_b32_e32 v62, v62, v0
	v_lshl_add_u64 v[60:61], v[60:61], 2, s[12:13]
	v_lshl_add_u64 v[62:63], v[62:63], 2, s[12:13]
	global_load_dword v46, v[60:61], off
	global_load_dword v47, v[62:63], off
	v_add_u32_e32 v60, -5, v12
	v_cmp_lt_i32_e64 s[40:41], 15, v60
	s_nop 1
	v_cndmask_b32_e64 v61, 15, v235, s[40:41]
	v_add3_u32 v61, v3, v61, s0
	v_add_u32_e32 v61, 0xffffff7a, v61
	v_cndmask_b32_e64 v62, v61, v60, s[38:39]
	v_ashrrev_i32_e32 v63, 31, v62
	v_lshl_add_u64 v[62:63], s[24:25], 0, v[62:63]
	v_lshlrev_b64 v[62:63], 8, v[62:63]
	v_or_b32_e32 v60, v62, v6
	v_mov_b32_e32 v61, v63
	v_or_b32_e32 v62, v62, v0
	v_lshl_add_u64 v[60:61], v[60:61], 2, s[12:13]
	v_lshl_add_u64 v[62:63], v[62:63], 2, s[12:13]
	global_load_dword v48, v[60:61], off
	global_load_dword v49, v[62:63], off
	v_add_u32_e32 v60, -4, v12
	v_cmp_lt_i32_e64 s[40:41], 15, v60
	s_nop 1
	v_cndmask_b32_e64 v61, 15, v235, s[40:41]
	v_add3_u32 v61, v3, v61, s0
	v_add_u32_e32 v61, 0xffffff79, v61
	v_cndmask_b32_e64 v62, v61, v60, s[38:39]
	v_ashrrev_i32_e32 v63, 31, v62
	v_lshl_add_u64 v[62:63], s[24:25], 0, v[62:63]
	v_lshlrev_b64 v[62:63], 8, v[62:63]
	v_or_b32_e32 v60, v62, v6
	v_mov_b32_e32 v61, v63
	v_or_b32_e32 v62, v62, v0
	v_lshl_add_u64 v[60:61], v[60:61], 2, s[12:13]
	v_lshl_add_u64 v[62:63], v[62:63], 2, s[12:13]
	global_load_dword v50, v[60:61], off
	global_load_dword v51, v[62:63], off
	v_add_u32_e32 v60, -3, v12
	v_cmp_lt_i32_e64 s[40:41], 15, v60
	s_nop 1
	v_cndmask_b32_e64 v61, 15, v235, s[40:41]
	v_add3_u32 v61, v3, v61, s0
	v_add_u32_e32 v61, 0xffffff78, v61
	v_cndmask_b32_e64 v62, v61, v60, s[38:39]
	v_ashrrev_i32_e32 v63, 31, v62
	v_lshl_add_u64 v[62:63], s[24:25], 0, v[62:63]
	v_lshlrev_b64 v[62:63], 8, v[62:63]
	v_or_b32_e32 v60, v62, v6
	v_mov_b32_e32 v61, v63
	v_or_b32_e32 v62, v62, v0
	v_lshl_add_u64 v[60:61], v[60:61], 2, s[12:13]
	v_lshl_add_u64 v[62:63], v[62:63], 2, s[12:13]
	global_load_dword v52, v[60:61], off
	global_load_dword v53, v[62:63], off
	v_add_u32_e32 v60, -2, v12
	v_cmp_lt_i32_e64 s[40:41], 15, v60
	s_nop 1
	v_cndmask_b32_e64 v61, 15, v235, s[40:41]
	v_add3_u32 v61, v3, v61, s0
	v_add_u32_e32 v61, 0xffffff77, v61
	v_cndmask_b32_e64 v62, v61, v60, s[38:39]
	v_ashrrev_i32_e32 v63, 31, v62
	v_lshl_add_u64 v[62:63], s[24:25], 0, v[62:63]
	v_lshlrev_b64 v[62:63], 8, v[62:63]
	v_or_b32_e32 v60, v62, v6
	v_mov_b32_e32 v61, v63
	v_or_b32_e32 v62, v62, v0
	v_lshl_add_u64 v[60:61], v[60:61], 2, s[12:13]
	v_lshl_add_u64 v[62:63], v[62:63], 2, s[12:13]
	global_load_dword v54, v[60:61], off
	global_load_dword v55, v[62:63], off
	v_add_u32_e32 v60, -1, v12
	v_cmp_lt_i32_e64 s[40:41], 15, v60
	s_nop 1
	v_cndmask_b32_e64 v61, 15, v235, s[40:41]
	v_add3_u32 v61, v3, v61, s0
	v_add_u32_e32 v61, 0xffffff76, v61
	v_cndmask_b32_e64 v62, v61, v60, s[38:39]
	v_ashrrev_i32_e32 v63, 31, v62
	v_lshl_add_u64 v[62:63], s[24:25], 0, v[62:63]
	v_lshlrev_b64 v[62:63], 8, v[62:63]
	v_or_b32_e32 v60, v62, v6
	v_mov_b32_e32 v61, v63
	v_or_b32_e32 v62, v62, v0
	v_lshl_add_u64 v[60:61], v[60:61], 2, s[12:13]
	v_lshl_add_u64 v[62:63], v[62:63], 2, s[12:13]
	global_load_dword v56, v[60:61], off
	global_load_dword v57, v[62:63], off
	v_mov_b32_e32 v60, v12
	v_cmp_lt_i32_e64 s[40:41], 15, v60
	s_nop 1
	v_cndmask_b32_e64 v61, 15, v235, s[40:41]
	v_add3_u32 v61, v3, v61, s0
	v_add_u32_e32 v61, 0xffffff75, v61
	v_cndmask_b32_e64 v62, v61, v60, s[38:39]
	v_ashrrev_i32_e32 v63, 31, v62
	v_lshl_add_u64 v[62:63], s[24:25], 0, v[62:63]
; DEVI bf16_t f2bf(float x) { return (bf16_t)(cvtpk(x, x) & 0xffffu); }
; DEVI void s5_carry_phase(const Params& p, char* lds) {
;     ...
; #pragma unroll 10
;     for (int i = 0; i < 130; ++i) {
;       const int pos = w * 130 + i;
;       const int c = dir == 0 ? pos : (pos < 16 ? 15 - pos : 1055 - pos);
;       const size_t o = base + (size_t)c * 256;
;       const float lr = SLOC[o + nre], li = SLOC[o + nim];
;       SIN[o + nre] = f2bf(sr); SIN[o + nim] = f2bf(si);
;       const float nr = a16.x * sr - a16.y * si + lr, ni = a16.x * si + a16.y * sr + li; sr = nr; si = ni;
;     }
	v_lshlrev_b64 v[62:63], 8, v[62:63]
	v_or_b32_e32 v60, v62, v6
	v_mov_b32_e32 v61, v63
	v_or_b32_e32 v62, v62, v0
	v_lshl_add_u64 v[60:61], v[60:61], 2, s[12:13]
	v_lshl_add_u64 v[62:63], v[62:63], 2, s[12:13]
	global_load_dword v58, v[60:61], off
	global_load_dword v59, v[62:63], off
	v_add_u32_e32 v13, -9, v12
	v_cmp_lt_i32_e64 s[40:41], 15, v13
	s_nop 1
	v_cndmask_b32_e64 v14, 15, v235, s[40:41]
	v_add3_u32 v14, v3, v14, s0
	v_add_u32_e32 v14, 0xffffff7e, v14
	v_cndmask_b32_e64 v14, v14, v13, s[38:39]
	v_ashrrev_i32_e32 v15, 31, v14
	v_lshl_add_u64 v[14:15], s[24:25], 0, v[14:15]
	v_lshlrev_b64 v[14:15], 8, v[14:15]
	v_or_b32_e32 v16, v14, v6
	v_mov_b32_e32 v17, v15
	v_or_b32_e32 v14, v14, v0
	v_lshl_add_u64 v[22:23], v[16:17], 2, s[12:13]
	v_lshl_add_u64 v[24:25], v[14:15], 2, s[12:13]
	v_cvt_pk_bf16_f32 v13, v10, v10
	v_lshl_add_u64 v[16:17], v[16:17], 1, s[14:15]
	global_store_short v[16:17], v13, off
	v_cvt_pk_bf16_f32 v13, v11, v11
	v_lshl_add_u64 v[14:15], v[14:15], 1, s[14:15]
	global_store_short v[14:15], v13, off
	v_add_u32_e32 v13, -8, v12
	v_pk_mul_f32 v[14:15], v[8:9], v[10:11] op_sel:[0,1]
	v_cmp_lt_i32_e64 s[40:41], 15, v13
	v_pk_fma_f32 v[16:17], v[4:5], v[10:11], v[14:15] neg_lo:[0,0,1] neg_hi:[0,0,1]
	v_pk_fma_f32 v[10:11], v[4:5], v[10:11], v[14:15] op_sel_hi:[1,0,1]
	v_cndmask_b32_e64 v14, 15, v235, s[40:41]
	v_add3_u32 v14, v3, v14, s0
	v_add_u32_e32 v14, 0xffffff7d, v14
	v_cndmask_b32_e64 v14, v14, v13, s[38:39]
	v_ashrrev_i32_e32 v15, 31, v14
	v_lshl_add_u64 v[14:15], s[24:25], 0, v[14:15]
	v_mov_b32_e32 v17, v11
	v_lshlrev_b64 v[14:15], 8, v[14:15]
	s_waitcnt vmcnt(20)
	v_pk_add_f32 v[10:11], v[16:17], v[40:41]
	v_or_b32_e32 v16, v14, v6
	v_mov_b32_e32 v17, v15
	v_or_b32_e32 v14, v14, v0
	v_lshl_add_u64 v[22:23], v[16:17], 2, s[12:13]
	v_lshl_add_u64 v[24:25], v[14:15], 2, s[12:13]
	v_cvt_pk_bf16_f32 v13, v10, v10
	v_lshl_add_u64 v[16:17], v[16:17], 1, s[14:15]
	global_store_short v[16:17], v13, off
	v_cvt_pk_bf16_f32 v13, v11, v11
	v_lshl_add_u64 v[14:15], v[14:15], 1, s[14:15]
	global_store_short v[14:15], v13, off
	v_add_u32_e32 v13, -7, v12
	v_pk_mul_f32 v[14:15], v[8:9], v[10:11] op_sel:[0,1]
	v_cmp_lt_i32_e64 s[40:41], 15, v13
	v_pk_fma_f32 v[16:17], v[4:5], v[10:11], v[14:15] neg_lo:[0,0,1] neg_hi:[0,0,1]
	v_pk_fma_f32 v[10:11], v[4:5], v[10:11], v[14:15] op_sel_hi:[1,0,1]
	v_cndmask_b32_e64 v14, 15, v235, s[40:41]
	v_add3_u32 v14, v3, v14, s0
	v_add_u32_e32 v14, 0xffffff7c, v14
	v_cndmask_b32_e64 v14, v14, v13, s[38:39]
	v_ashrrev_i32_e32 v15, 31, v14
	v_lshl_add_u64 v[14:15], s[24:25], 0, v[14:15]
	v_mov_b32_e32 v17, v11
	v_lshlrev_b64 v[14:15], 8, v[14:15]
	s_waitcnt vmcnt(20)
	v_pk_add_f32 v[10:11], v[16:17], v[42:43]
	v_or_b32_e32 v16, v14, v6
	v_mov_b32_e32 v17, v15
	v_or_b32_e32 v14, v14, v0
	v_lshl_add_u64 v[22:23], v[16:17], 2, s[12:13]
	v_lshl_add_u64 v[24:25], v[14:15], 2, s[12:13]
	v_cvt_pk_bf16_f32 v13, v10, v10
	v_lshl_add_u64 v[16:17], v[16:17], 1, s[14:15]
	global_store_short v[16:17], v13, off
	v_cvt_pk_bf16_f32 v13, v11, v11
	v_lshl_add_u64 v[14:15], v[14:15], 1, s[14:15]
	global_store_short v[14:15], v13, off
	v_add_u32_e32 v13, -6, v12
	v_pk_mul_f32 v[14:15], v[8:9], v[10:11] op_sel:[0,1]
	v_cmp_lt_i32_e64 s[40:41], 15, v13
	v_pk_fma_f32 v[16:17], v[4:5], v[10:11], v[14:15] neg_lo:[0,0,1] neg_hi:[0,0,1]
	v_pk_fma_f32 v[10:11], v[4:5], v[10:11], v[14:15] op_sel_hi:[1,0,1]
	v_cndmask_b32_e64 v14, 15, v235, s[40:41]
	v_add3_u32 v14, v3, v14, s0
	v_add_u32_e32 v14, 0xffffff7b, v14
	v_cndmask_b32_e64 v14, v14, v13, s[38:39]
	v_ashrrev_i32_e32 v15, 31, v14
	v_lshl_add_u64 v[14:15], s[24:25], 0, v[14:15]
	v_mov_b32_e32 v17, v11
	v_lshlrev_b64 v[14:15], 8, v[14:15]
	s_waitcnt vmcnt(20)
	v_pk_add_f32 v[10:11], v[16:17], v[44:45]
	v_or_b32_e32 v16, v14, v6
	v_mov_b32_e32 v17, v15
	v_or_b32_e32 v14, v14, v0
	v_lshl_add_u64 v[22:23], v[16:17], 2, s[12:13]
	v_lshl_add_u64 v[24:25], v[14:15], 2, s[12:13]
	v_cvt_pk_bf16_f32 v13, v10, v10
	v_lshl_add_u64 v[16:17], v[16:17], 1, s[14:15]
	global_store_short v[16:17], v13, off
	v_cvt_pk_bf16_f32 v13, v11, v11
	v_lshl_add_u64 v[14:15], v[14:15], 1, s[14:15]
	global_store_short v[14:15], v13, off
	v_add_u32_e32 v13, -5, v12
	v_pk_mul_f32 v[14:15], v[8:9], v[10:11] op_sel:[0,1]
	v_cmp_lt_i32_e64 s[40:41], 15, v13
	v_pk_fma_f32 v[16:17], v[4:5], v[10:11], v[14:15] neg_lo:[0,0,1] neg_hi:[0,0,1]
	v_pk_fma_f32 v[10:11], v[4:5], v[10:11], v[14:15] op_sel_hi:[1,0,1]
	v_cndmask_b32_e64 v14, 15, v235, s[40:41]
	v_add3_u32 v14, v3, v14, s0
	v_add_u32_e32 v14, 0xffffff7a, v14
	v_cndmask_b32_e64 v14, v14, v13, s[38:39]
	v_ashrrev_i32_e32 v15, 31, v14
	v_lshl_add_u64 v[14:15], s[24:25], 0, v[14:15]
	v_mov_b32_e32 v17, v11
	v_lshlrev_b64 v[14:15], 8, v[14:15]
	s_waitcnt vmcnt(20)
	v_pk_add_f32 v[10:11], v[16:17], v[46:47]
	v_or_b32_e32 v16, v14, v6
	v_mov_b32_e32 v17, v15
	v_or_b32_e32 v14, v14, v0
	v_lshl_add_u64 v[22:23], v[16:17], 2, s[12:13]
	v_lshl_add_u64 v[24:25], v[14:15], 2, s[12:13]
	v_cvt_pk_bf16_f32 v13, v10, v10
	v_lshl_add_u64 v[16:17], v[16:17], 1, s[14:15]
	global_store_short v[16:17], v13, off
	v_cvt_pk_bf16_f32 v13, v11, v11
	v_lshl_add_u64 v[14:15], v[14:15], 1, s[14:15]
	global_store_short v[14:15], v13, off
	v_add_u32_e32 v13, -4, v12
	v_pk_mul_f32 v[14:15], v[8:9], v[10:11] op_sel:[0,1]
	v_cmp_lt_i32_e64 s[40:41], 15, v13
	v_pk_fma_f32 v[16:17], v[4:5], v[10:11], v[14:15] neg_lo:[0,0,1] neg_hi:[0,0,1]
	v_pk_fma_f32 v[10:11], v[4:5], v[10:11], v[14:15] op_sel_hi:[1,0,1]
	v_cndmask_b32_e64 v14, 15, v235, s[40:41]
	v_add3_u32 v14, v3, v14, s0
	v_add_u32_e32 v14, 0xffffff79, v14
	v_cndmask_b32_e64 v14, v14, v13, s[38:39]
	v_ashrrev_i32_e32 v15, 31, v14
	v_lshl_add_u64 v[14:15], s[24:25], 0, v[14:15]
	v_mov_b32_e32 v17, v11
	v_lshlrev_b64 v[14:15], 8, v[14:15]
	s_waitcnt vmcnt(20)
; DEVI bf16_t f2bf(float x) { return (bf16_t)(cvtpk(x, x) & 0xffffu); }
; DEVI void s5_carry_phase(const Params& p, char* lds) {
;     ...
; #pragma unroll 10
;     for (int i = 0; i < 130; ++i) {
;       const int pos = w * 130 + i;
;       const int c = dir == 0 ? pos : (pos < 16 ? 15 - pos : 1055 - pos);
;       const size_t o = base + (size_t)c * 256;
;       const float lr = SLOC[o + nre], li = SLOC[o + nim];
;       SIN[o + nre] = f2bf(sr); SIN[o + nim] = f2bf(si);
;       const float nr = a16.x * sr - a16.y * si + lr, ni = a16.x * si + a16.y * sr + li; sr = nr; si = ni;
;     }
	v_pk_add_f32 v[10:11], v[16:17], v[48:49]
	v_or_b32_e32 v16, v14, v6
	v_mov_b32_e32 v17, v15
	v_or_b32_e32 v14, v14, v0
	v_lshl_add_u64 v[22:23], v[16:17], 2, s[12:13]
	v_lshl_add_u64 v[24:25], v[14:15], 2, s[12:13]
	v_cvt_pk_bf16_f32 v13, v10, v10
	v_lshl_add_u64 v[16:17], v[16:17], 1, s[14:15]
	global_store_short v[16:17], v13, off
	v_cvt_pk_bf16_f32 v13, v11, v11
	v_lshl_add_u64 v[14:15], v[14:15], 1, s[14:15]
	global_store_short v[14:15], v13, off
	v_add_u32_e32 v13, -3, v12
	v_pk_mul_f32 v[14:15], v[8:9], v[10:11] op_sel:[0,1]
	v_cmp_lt_i32_e64 s[40:41], 15, v13
	v_pk_fma_f32 v[16:17], v[4:5], v[10:11], v[14:15] neg_lo:[0,0,1] neg_hi:[0,0,1]
	v_pk_fma_f32 v[10:11], v[4:5], v[10:11], v[14:15] op_sel_hi:[1,0,1]
	v_cndmask_b32_e64 v14, 15, v235, s[40:41]
	v_add3_u32 v14, v3, v14, s0
	v_add_u32_e32 v14, 0xffffff78, v14
	v_cndmask_b32_e64 v14, v14, v13, s[38:39]
	v_ashrrev_i32_e32 v15, 31, v14
	v_lshl_add_u64 v[14:15], s[24:25], 0, v[14:15]
	v_mov_b32_e32 v17, v11
	v_lshlrev_b64 v[14:15], 8, v[14:15]
	s_waitcnt vmcnt(20)
	v_pk_add_f32 v[10:11], v[16:17], v[50:51]
	v_or_b32_e32 v16, v14, v6
	v_mov_b32_e32 v17, v15
	v_or_b32_e32 v14, v14, v0
	v_lshl_add_u64 v[22:23], v[16:17], 2, s[12:13]
	v_lshl_add_u64 v[24:25], v[14:15], 2, s[12:13]
	v_cvt_pk_bf16_f32 v13, v10, v10
	v_lshl_add_u64 v[16:17], v[16:17], 1, s[14:15]
	global_store_short v[16:17], v13, off
	v_cvt_pk_bf16_f32 v13, v11, v11
	v_lshl_add_u64 v[14:15], v[14:15], 1, s[14:15]
	global_store_short v[14:15], v13, off
	v_add_u32_e32 v13, -2, v12
	v_pk_mul_f32 v[14:15], v[8:9], v[10:11] op_sel:[0,1]
	v_cmp_lt_i32_e64 s[40:41], 15, v13
	v_pk_fma_f32 v[16:17], v[4:5], v[10:11], v[14:15] neg_lo:[0,0,1] neg_hi:[0,0,1]
	v_pk_fma_f32 v[10:11], v[4:5], v[10:11], v[14:15] op_sel_hi:[1,0,1]
	v_cndmask_b32_e64 v14, 15, v235, s[40:41]
	v_add3_u32 v14, v3, v14, s0
	v_add_u32_e32 v14, 0xffffff77, v14
	v_cndmask_b32_e64 v14, v14, v13, s[38:39]
	v_ashrrev_i32_e32 v15, 31, v14
	v_lshl_add_u64 v[14:15], s[24:25], 0, v[14:15]
	v_mov_b32_e32 v17, v11
	v_lshlrev_b64 v[14:15], 8, v[14:15]
	s_waitcnt vmcnt(20)
	v_pk_add_f32 v[10:11], v[16:17], v[52:53]
	v_or_b32_e32 v16, v14, v6
	v_mov_b32_e32 v17, v15
	v_or_b32_e32 v14, v14, v0
	v_lshl_add_u64 v[22:23], v[16:17], 2, s[12:13]
	v_lshl_add_u64 v[24:25], v[14:15], 2, s[12:13]
	v_cvt_pk_bf16_f32 v13, v10, v10
	v_lshl_add_u64 v[16:17], v[16:17], 1, s[14:15]
	global_store_short v[16:17], v13, off
	v_cvt_pk_bf16_f32 v13, v11, v11
	v_lshl_add_u64 v[14:15], v[14:15], 1, s[14:15]
	global_store_short v[14:15], v13, off
	v_add_u32_e32 v13, -1, v12
	v_pk_mul_f32 v[14:15], v[8:9], v[10:11] op_sel:[0,1]
	v_cmp_lt_i32_e64 s[40:41], 15, v13
	v_pk_fma_f32 v[16:17], v[4:5], v[10:11], v[14:15] neg_lo:[0,0,1] neg_hi:[0,0,1]
	v_pk_fma_f32 v[10:11], v[4:5], v[10:11], v[14:15] op_sel_hi:[1,0,1]
	v_cndmask_b32_e64 v14, 15, v235, s[40:41]
	v_add3_u32 v14, v3, v14, s0
	v_add_u32_e32 v14, 0xffffff76, v14
	v_cndmask_b32_e64 v14, v14, v13, s[38:39]
	v_ashrrev_i32_e32 v15, 31, v14
	v_lshl_add_u64 v[14:15], s[24:25], 0, v[14:15]
	v_mov_b32_e32 v17, v11
	v_lshlrev_b64 v[14:15], 8, v[14:15]
	v_cmp_lt_i32_e64 s[40:41], 15, v12
	s_waitcnt vmcnt(20)
	v_pk_add_f32 v[10:11], v[16:17], v[54:55]
	v_or_b32_e32 v16, v14, v6
	v_mov_b32_e32 v17, v15
	v_or_b32_e32 v14, v14, v0
	v_lshl_add_u64 v[22:23], v[16:17], 2, s[12:13]
	v_lshl_add_u64 v[24:25], v[14:15], 2, s[12:13]
	v_cvt_pk_bf16_f32 v13, v10, v10
	v_lshl_add_u64 v[16:17], v[16:17], 1, s[14:15]
	global_store_short v[16:17], v13, off
	v_cvt_pk_bf16_f32 v13, v11, v11
	v_lshl_add_u64 v[14:15], v[14:15], 1, s[14:15]
	global_store_short v[14:15], v13, off
	v_cndmask_b32_e64 v13, 15, v235, s[40:41]
	v_add3_u32 v13, v3, v13, s0
	v_pk_mul_f32 v[14:15], v[8:9], v[10:11] op_sel:[0,1]
	v_add_u32_e32 v13, 0xffffff75, v13
	v_pk_fma_f32 v[16:17], v[4:5], v[10:11], v[14:15] neg_lo:[0,0,1] neg_hi:[0,0,1]
	v_pk_fma_f32 v[10:11], v[4:5], v[10:11], v[14:15] op_sel_hi:[1,0,1]
	v_cndmask_b32_e64 v14, v13, v12, s[38:39]
	v_ashrrev_i32_e32 v15, 31, v14
	v_lshl_add_u64 v[14:15], s[24:25], 0, v[14:15]
	v_mov_b32_e32 v17, v11
	v_lshlrev_b64 v[14:15], 8, v[14:15]
	s_add_i32 s0, s0, -10
	v_add_u32_e32 v12, 10, v12
	s_cmp_eq_u32 s0, 0
	s_waitcnt vmcnt(20)
	v_pk_add_f32 v[10:11], v[16:17], v[56:57]
	v_or_b32_e32 v16, v14, v6
	v_mov_b32_e32 v17, v15
	v_or_b32_e32 v14, v14, v0
	v_lshl_add_u64 v[22:23], v[16:17], 2, s[12:13]
	v_lshl_add_u64 v[24:25], v[14:15], 2, s[12:13]
	v_cvt_pk_bf16_f32 v13, v10, v10
	v_lshl_add_u64 v[16:17], v[16:17], 1, s[14:15]
	v_lshl_add_u64 v[14:15], v[14:15], 1, s[14:15]
	global_store_short v[16:17], v13, off
	v_cvt_pk_bf16_f32 v13, v11, v11
	global_store_short v[14:15], v13, off
	v_pk_mul_f32 v[14:15], v[8:9], v[10:11] op_sel:[0,1]
	s_nop 0
	v_pk_fma_f32 v[16:17], v[4:5], v[10:11], v[14:15] neg_lo:[0,0,1] neg_hi:[0,0,1]
	v_pk_fma_f32 v[10:11], v[4:5], v[10:11], v[14:15] op_sel_hi:[1,0,1]
	s_nop 0
	v_mov_b32_e32 v17, v11
	s_waitcnt vmcnt(20)
	v_pk_add_f32 v[10:11], v[16:17], v[58:59]
	s_cbranch_scc0 .LBB0_2121
	s_mov_b32 s0, s86
	s_add_i32 s35, s0, s35
	s_cmpk_gt_i32 s35, 0x7f
	s_cbranch_scc0 .LBB0_2114
